# r48 + gdn_scan: loop-invariant norm-gain load hoisted out of the chunk loop (removes a vmcnt(0) drain of the next chunk's prefetch loads before the output-norm work each chunk)
# speedup vs baseline: 1.0048x; 1.0025x over previous
.LBB0_905:
	s_or_b64 exec, exec, s[24:25]
	v_ashrrev_i32_e32 v3, 9, v4
	v_mul_i32_i24_e32 v197, 0x2200, v3
	v_lshlrev_b32_e32 v3, 4, v2
	v_add_u32_e32 v6, 0x100, v2
	v_bfe_u32 v5, v4, 3, 6
	v_and_b32_e32 v150, 0x70, v3
	v_ashrrev_i32_e32 v3, 9, v6
	s_waitcnt vmcnt(2)
	v_add_u32_e32 v8, 0x280, v2
	v_mul_u32_u24_e32 v198, 0x88, v5
	v_bfe_u32 v5, v6, 3, 6
	v_mul_i32_i24_e32 v199, 0x2200, v3
	v_ashrrev_i32_e32 v3, 9, v8
	v_add_u32_e32 v10, 0x400, v2
	v_mul_u32_u24_e32 v200, 0x88, v5
	v_bfe_u32 v5, v8, 3, 6
	v_mul_i32_i24_e32 v201, 0x2200, v3
	v_ashrrev_i32_e32 v3, 9, v10
	v_add_u32_e32 v12, 0x580, v2
	v_mul_u32_u24_e32 v202, 0x88, v5
	v_bfe_u32 v5, v2, 3, 6
	v_mul_i32_i24_e32 v203, 0x2200, v3
	v_ashrrev_i32_e32 v3, 9, v12
	v_add_u32_e32 v14, 0x700, v2
	v_mul_u32_u24_e32 v204, 0x88, v5
	v_mul_i32_i24_e32 v205, 0x2200, v3
	v_ashrrev_i32_e32 v3, 9, v14
	v_bfe_u32 v5, v14, 3, 6
	s_waitcnt vmcnt(1)
	v_add_u32_e32 v16, 0x880, v2
	v_mul_i32_i24_e32 v206, 0x2200, v3
	v_mul_u32_u24_e32 v207, 0x88, v5
	v_ashrrev_i32_e32 v3, 9, v16
	v_bfe_u32 v5, v16, 3, 6
	v_ashrrev_i32_e32 v18, 3, v4
	s_waitcnt vmcnt(0)
	v_ashrrev_i32_e32 v20, 3, v6
	v_mul_i32_i24_e32 v208, 0x2200, v3
	v_mul_u32_u24_e32 v209, 0x88, v5
	v_ashrrev_i32_e32 v5, 31, v4
	s_lshl_b64 s[20:21], s[2:3], 11
	v_ashrrev_i32_e32 v19, 31, v18
	v_ashrrev_i32_e32 v21, 31, v20
	v_lshlrev_b32_e32 v3, 2, v2
	v_lshlrev_b64 v[152:153], 4, v[4:5]
	v_ashrrev_i32_e32 v7, 31, v6
	v_lshl_add_u64 v[170:171], s[20:21], 0, v[18:19]
	v_lshl_add_u64 v[172:173], s[20:21], 0, v[20:21]
	v_ashrrev_i32_e32 v148, 4, v4
	v_and_b32_e32 v3, 60, v3
	s_lshl_b64 s[20:21], s[2:3], 22
	v_and_b32_e32 v4, 31, v2
	v_readlane_b32 s2, v254, 27
	s_movk_i32 s24, 0x88
	v_lshlrev_b64 v[154:155], 4, v[6:7]
	v_bfe_u32 v6, v2, 5, 1
	v_lshl_or_b32 v1, v1, 5, v4
	v_mul_u32_u24_e32 v215, 0x88, v4
	v_lshlrev_b32_e32 v4, 2, v3
	v_mov_b32_e32 v5, v0
	v_readlane_b32 s3, v254, 28
	v_lshlrev_b32_e32 v212, 1, v3
	v_mul_lo_u32 v213, v1, s24
	v_lshlrev_b32_e32 v1, 2, v1
	v_lshl_add_u64 v[174:175], s[2:3], 0, v[4:5]
	global_load_dwordx4 v[240:243], v[174:175], off
	v_mul_u32_u24_e32 v3, 0x410, v6
	v_readlane_b32 s2, v253, 24
	v_mov_b32_e32 v151, v0
	s_movk_i32 s4, 0xa80
	v_add3_u32 v216, s2, v1, v3
	s_lshl_b32 s2, s30, 7
	s_add_u32 s2, s58, s2
	s_addc_u32 s3, s59, 0
	v_lshl_add_u64 v[178:179], s[2:3], 0, v[150:151]
	s_movk_i32 s2, 0x104
	v_mul_lo_u32 v1, v148, s2
	s_lshl_b32 s2, s31, 7
	v_readlane_b32 s18, v253, 57
	s_and_b32 s30, s2, 0x180
	v_cmp_gt_i32_e32 vcc, s4, v2
	s_movk_i32 s4, 0x900
	s_movk_i32 s6, 0x780
	s_movk_i32 s8, 0x600
	s_movk_i32 s12, 0x300
	s_movk_i32 s14, 0x180
	s_movk_i32 s16, 0x280
	v_readlane_b32 s19, v253, 58
	s_or_b32 s2, s20, s30
	v_cmp_gt_i32_e64 s[4:5], s4, v2
	v_cmp_gt_i32_e64 s[6:7], s6, v2
	v_cmp_gt_i32_e64 s[8:9], s8, v2
	v_cmp_gt_i32_e64 s[10:11], s38, v2
	v_cmp_gt_i32_e64 s[12:13], s12, v2
	v_cmp_gt_i32_e64 s[14:15], s14, v2
	v_cmp_gt_i32_e64 s[16:17], s16, v2
	v_cmp_gt_i32_e64 s[18:19], s18, v2
	v_ashrrev_i32_e32 v15, 31, v14
	v_and_b32_e32 v2, 15, v2
	s_add_u32 s2, s62, s2
	v_ashrrev_i32_e32 v9, 31, v8
	v_ashrrev_i32_e32 v11, 31, v10
	v_ashrrev_i32_e32 v13, 31, v12
	v_lshlrev_b64 v[166:167], 4, v[14:15]
	v_ashrrev_i32_e32 v17, 31, v16
	v_lshlrev_b32_e32 v176, 3, v2
	v_mov_b32_e32 v177, v0
	s_addc_u32 s3, s63, s21
	v_mov_b32_e32 v14, v0
	v_mov_b32_e32 v15, v0
	v_mul_lo_u32 v210, v18, s24
	v_mul_lo_u32 v211, v20, s24
	v_lshlrev_b64 v[156:157], 4, v[8:9]
	v_lshlrev_b64 v[158:159], 4, v[10:11]
	v_lshlrev_b64 v[160:161], 4, v[12:13]
	v_lshlrev_b64 v[168:169], 4, v[16:17]
	v_lshlrev_b32_e32 v214, 3, v6
	v_lshl_add_u32 v151, v2, 4, v1
	v_lshl_add_u64 v[180:181], s[2:3], 0, v[176:177]
	v_mul_lo_u32 v217, v148, s24
	s_mov_b32 s2, 0x1d600
	v_mov_b32_e32 v1, v0
	v_mov_b32_e32 v2, v0
	v_mov_b32_e32 v3, v0
	v_mov_b32_e32 v4, v0
	v_mov_b32_e32 v6, v0
	v_mov_b32_e32 v7, v0
	v_mov_b32_e32 v8, v0
	v_mov_b32_e32 v9, v0
	v_mov_b32_e32 v10, v0
	v_mov_b32_e32 v11, v0
	v_mov_b32_e32 v12, v0
	v_mov_b32_e32 v13, v0
	v_mov_b64_e32 v[30:31], v[14:15]
	v_mov_b64_e32 v[46:47], v[14:15]
	v_ashrrev_i32_e32 v149, 31, v148
	v_add3_u32 v218, v217, v212, s2
	s_mov_b32 s31, 0
	s_movk_i32 s24, 0xffc0
	s_movk_i32 s34, 0xff
	v_mov_b64_e32 v[28:29], v[12:13]
	v_mov_b64_e32 v[26:27], v[10:11]
	v_mov_b64_e32 v[24:25], v[8:9]
	v_mov_b64_e32 v[22:23], v[6:7]
	v_mov_b64_e32 v[20:21], v[4:5]
	v_mov_b64_e32 v[18:19], v[2:3]
	v_mov_b64_e32 v[16:17], v[0:1]
	v_mov_b64_e32 v[44:45], v[12:13]
	v_mov_b64_e32 v[42:43], v[10:11]
	v_mov_b64_e32 v[40:41], v[8:9]
	v_mov_b64_e32 v[38:39], v[6:7]
	v_mov_b64_e32 v[36:37], v[4:5]
	v_mov_b64_e32 v[34:35], v[2:3]
	v_mov_b64_e32 v[32:33], v[0:1]
	s_waitcnt lgkmcnt(0)
	s_waitcnt vmcnt(0)
	s_barrier
	s_branch .LBB0_907

.LBB0_935:
	s_mov_b32 s25, s89
	v_lshl_add_u64 v[2:3], v[148:149], 0, s[24:25]
	v_lshlrev_b64 v[2:3], 11, v[2:3]
	v_lshl_add_u64 v[6:7], v[180:181], 0, v[2:3]
	s_and_b32 s2, s34, 0xff
	s_mul_i32 s3, s2, 0x2200
	s_mul_hi_u32 s2, s2, 0x55555556
	v_add_u32_e32 v1, s3, v218
	s_mulk_i32 s2, 0x6600
	s_bitcmp1_b32 s31, 0
	v_subrev_u32_e32 v1, s2, v1
	s_cselect_b32 s2, 0, 0x4100
	s_mov_b32 s25, 0
	v_add_u32_e32 v8, s2, v151
	s_branch .LBB0_937

.LBB0_937:
	v_add_u32_e32 v9, s25, v148
	v_cmp_gt_i32_e64 s[2:3], 64, v9
	s_and_saveexec_b64 s[28:29], s[2:3]
	s_cbranch_execz .LBB0_936
	v_add_u32_e32 v9, 0, v8
	v_add_u32_e32 v10, 0x15408, v9
	v_add_u32_e32 v12, 0, v1
	ds_read2_b32 v[10:11], v10 offset1:1
	ds_read_b64 v[12:13], v12
	v_add_u32_e32 v9, 0x15400, v9
	ds_read2_b32 v[14:15], v9 offset1:1
	s_waitcnt lgkmcnt(2)
	v_pk_mul_f32 v[48:49], v[10:11], v[10:11]
	s_waitcnt lgkmcnt(1)
	v_lshlrev_b32_e32 v50, 16, v12
	v_and_b32_e32 v51, 0xffff0000, v12
	v_mul_f32_e32 v9, 0xbfb8aa3b, v50
	v_exp_f32_e32 v9, v9
	v_mul_f32_e32 v12, 0xbfb8aa3b, v51
	v_exp_f32_e32 v12, v12
	s_waitcnt lgkmcnt(0)
	v_pk_mul_f32 v[52:53], v[14:15], v[14:15]
	v_add_f32_e32 v9, 1.0, v9
	v_rcp_f32_e32 v54, v9
	v_add_f32_e32 v9, 1.0, v12
	v_rcp_f32_e32 v55, v9
	v_add_f32_e32 v9, v52, v53
	v_add_f32_e32 v9, v9, v48
	v_add_f32_e32 v9, v9, v49
	v_pk_mul_f32 v[48:49], v[54:55], v[50:51]
	v_lshlrev_b32_e32 v50, 16, v13
	v_add_f32_dpp v9, v9, v9 quad_perm:[1,0,3,2] row_mask:0xf bank_mask:0xf bound_ctrl:1
	v_and_b32_e32 v51, 0xffff0000, v13
	s_nop 0
	v_add_f32_dpp v9, v9, v9 quad_perm:[2,3,0,1] row_mask:0xf bank_mask:0xf bound_ctrl:1
	s_nop 1
	v_add_f32_dpp v9, v9, v9 row_half_mirror row_mask:0xf bank_mask:0xf bound_ctrl:1
	s_nop 1
	v_add_f32_dpp v9, v9, v9 row_mirror row_mask:0xf bank_mask:0xf bound_ctrl:1
	v_fmamk_f32 v9, v9, 0x3c800000, v184
	v_mul_f32_e32 v12, 0x4b800000, v9
	v_cmp_gt_f32_e64 s[2:3], s72, v9
	s_nop 1
	v_cndmask_b32_e64 v9, v9, v12, s[2:3]
	v_rsq_f32_e32 v9, v9
	s_nop 0
	v_mul_f32_e32 v12, 0x45800000, v9
	v_cndmask_b32_e64 v12, v9, v12, s[2:3]
	v_mul_f32_e32 v9, 0xbfb8aa3b, v50
	v_pk_mul_f32 v[14:15], v[14:15], v[12:13] op_sel_hi:[1,0]
	v_exp_f32_e32 v9, v9
	v_mul_f32_e32 v13, 0xbfb8aa3b, v51
	v_exp_f32_e32 v13, v13
	v_pk_mul_f32 v[14:15], v[240:241], v[14:15]
	v_add_f32_e32 v9, 1.0, v9
	v_rcp_f32_e32 v52, v9
	v_add_f32_e32 v9, 1.0, v13
	v_rcp_f32_e32 v53, v9
	v_pk_mul_f32 v[10:11], v[10:11], v[12:13] op_sel_hi:[1,0]
	v_pk_mul_f32 v[14:15], v[48:49], v[14:15]
	v_pk_mul_f32 v[10:11], v[242:243], v[10:11]
	v_pk_mul_f32 v[12:13], v[52:53], v[50:51]
	s_nop 0
	v_pk_mul_f32 v[10:11], v[12:13], v[10:11]
	v_cvt_pk_bf16_f32 v12, v14, v15
	v_cvt_pk_bf16_f32 v13, v10, v11
	global_store_dwordx2 v[6:7], v[12:13], off
	s_branch .LBB0_936
